# every 32-MFMA run starts on an 8-byte boundary (one s_nop added in the preceding load segment where needed, 7 sites)
# speedup vs baseline: 1.0019x; 1.0019x over previous
; #define PG8_STAGE(bufoff, gbase, voff) do { _Pragma("unroll") for (int _i = 0; _i < 2; ++_i) \
;         __builtin_amdgcn_global_load_lds((const unsigned*)((const char*)(gbase) + (voff)[_i]), (LAS unsigned*)(lds + (bufoff) + ldsw + _i * 8192), 16, 0, 0); } while (0)
; #define PG8_LDA(dst, b, h) do { _Pragma("unroll") for (int m = 0; m < 4; ++m) _Pragma("unroll") for (int k = 0; k < 2; ++k) dst[m][k] = *(const LAS bf16x8*)(lds + PG8_SA(b, h) + aoff + m * 2048 + k * 1024); } while (0)
; #define PG8_LDB(dst, b, h) do { _Pragma("unroll") for (int n = 0; n < 2; ++n) _Pragma("unroll") for (int k = 0; k < 2; ++k) dst[n][k] = *(const LAS bf16x8*)(lds + PG8_SB(b, h) + boff + n * 2048 + k * 1024); } while (0)
; #define PG8_MMA(ai, bj, At, Bt) do { __builtin_amdgcn_s_setprio(1); _Pragma("unroll") for (int m = 0; m < 4; ++m) _Pragma("unroll") for (int n = 0; n < 2; ++n) _Pragma("unroll") for (int k = 0; k < 2; ++k) \
;         acc[ai][bj][m][n] = __builtin_amdgcn_mfma_f32_16x16x32_bf16(Bt[n][k], At[m][k], acc[ai][bj][m][n], 0, 0, 0); __builtin_amdgcn_s_setprio(0); } while (0)
; #define PG8_WAIT_V(n) asm volatile("s_waitcnt vmcnt(" #n ")" ::: "memory")
; #define PG8_WAIT_L(n) asm volatile("s_waitcnt lgkmcnt(" #n ")" ::: "memory")
; #define PG8_BAR __builtin_amdgcn_s_barrier()
; #define PG8_SCHED __builtin_amdgcn_sched_barrier(0)
; template <class Epi>
; __device__ __forceinline__ void gemm_phase(LAS unsigned char* lds, const Gemm g, const StaticOrder& S, const Epi& E, const int tid) {
;     ...
;             PG8_LDB(B0, 0, 0); PG8_LDB(B1, 0, 1); PG8_SCHED; PG8_LDA(At, 0, 0); PG8_STAGE(PG8_SA(1, 1), a1 + hstepA, voffA);
;             PG8_WAIT_V(8); PG8_WAIT_L(0); PG8_BAR; PG8_MMA(0, 0, At, B0); PG8_MMA(0, 1, At, B1); PG8_BAR; PG8_SCHED;
.LBB0_183:
	v_mov_b32_e32 v137, 0
	s_andn2_b64 vcc, exec, s[96:97]
	s_cbranch_vccnz .LBB0_187
	s_add_u32 s0, s36, 0x100
	s_addc_u32 s1, s37, 0
	s_add_u32 s6, s38, 0x80
	s_addc_u32 s7, s39, 0
	s_mov_b32 s36, 0
	s_add_i32 s38, s36, 2
	s_add_u32 s39, s6, 0x80
	s_addc_u32 s37, s7, 0
	s_add_i32 s62, 0, 0x10000
	s_cmp_eq_u32 s53, s36
	s_cselect_b32 s37, s31, s37
	s_cselect_b32 s36, s30, s39
	s_cselect_b32 s61, s35, s1
	s_cselect_b32 s60, s34, s0
	s_add_i32 s39, 0, 0x14000
	v_add_u32_e32 v152, s62, v168
	v_add_u32_e32 v170, s39, v168
	ds_read_b128 v[82:85], v152
	ds_read_b128 v[86:89], v152 offset:1024
	ds_read_b128 v[138:141], v152 offset:2048
	ds_read_b128 v[152:155], v152 offset:3072
	ds_read_b128 v[156:159], v170
	ds_read_b128 v[160:163], v170 offset:1024
	ds_read_b128 v[164:167], v170 offset:2048
	ds_read_b128 v[170:173], v170 offset:3072
	v_lshl_add_u64 v[194:195], s[6:7], 0, v[150:151]
	s_add_i32 m0, s44, 0xc000
	ds_read_b128 v[174:177], v169
	ds_read_b128 v[178:181], v169 offset:1024
	ds_read_b128 v[182:185], v169 offset:2048
	ds_read_b128 v[186:189], v169 offset:3072
	ds_read_b128 v[190:193], v169 offset:4096
	ds_read_b128 v[202:205], v169 offset:5120
	ds_read_b128 v[206:209], v169 offset:6144
	ds_read_b128 v[210:213], v169 offset:7168
	global_load_lds_dwordx4 v[194:195], off
	v_lshl_add_u64 v[194:195], s[6:7], 0, v[148:149]
	s_add_i32 m0, s44, 0xe000
	s_nop 0
	global_load_lds_dwordx4 v[194:195], off
	s_waitcnt vmcnt(8)
	s_waitcnt lgkmcnt(0)
	s_nop 0
	s_barrier
	s_setprio 1
	s_waitcnt lgkmcnt(0)
	v_mfma_f32_16x16x32_bf16 v[134:137], v[82:85], v[174:177], 0
	v_mfma_f32_16x16x32_bf16 v[62:65], v[138:141], v[174:177], 0
	v_mfma_f32_16x16x32_bf16 v[126:129], v[82:85], v[182:185], 0
	v_mfma_f32_16x16x32_bf16 v[54:57], v[138:141], v[182:185], 0
	v_mfma_f32_16x16x32_bf16 v[118:121], v[82:85], v[190:193], 0
	v_mfma_f32_16x16x32_bf16 v[46:49], v[138:141], v[190:193], 0
	v_mfma_f32_16x16x32_bf16 v[110:113], v[82:85], v[206:209], 0
	v_mfma_f32_16x16x32_bf16 v[38:41], v[138:141], v[206:209], 0
	v_mfma_f32_16x16x32_bf16 v[134:137], v[86:89], v[178:181], v[134:137]
	v_mfma_f32_16x16x32_bf16 v[62:65], v[152:155], v[178:181], v[62:65]
	v_mfma_f32_16x16x32_bf16 v[126:129], v[86:89], v[186:189], v[126:129]
	v_mfma_f32_16x16x32_bf16 v[54:57], v[152:155], v[186:189], v[54:57]
	v_mfma_f32_16x16x32_bf16 v[118:121], v[86:89], v[202:205], v[118:121]
	v_mfma_f32_16x16x32_bf16 v[46:49], v[152:155], v[202:205], v[46:49]
	v_mfma_f32_16x16x32_bf16 v[110:113], v[86:89], v[210:213], v[110:113]
	v_mfma_f32_16x16x32_bf16 v[38:41], v[152:155], v[210:213], v[38:41]
	s_setprio 0
	s_setprio 1
	v_mfma_f32_16x16x32_bf16 v[130:133], v[156:159], v[174:177], 0
	v_mfma_f32_16x16x32_bf16 v[58:61], v[164:167], v[174:177], 0
	v_mfma_f32_16x16x32_bf16 v[122:125], v[156:159], v[182:185], 0
	v_mfma_f32_16x16x32_bf16 v[50:53], v[164:167], v[182:185], 0
	v_mfma_f32_16x16x32_bf16 v[114:117], v[156:159], v[190:193], 0
	v_mfma_f32_16x16x32_bf16 v[42:45], v[164:167], v[190:193], 0
	v_mfma_f32_16x16x32_bf16 v[106:109], v[156:159], v[206:209], 0
	v_mfma_f32_16x16x32_bf16 v[34:37], v[164:167], v[206:209], 0
	v_mfma_f32_16x16x32_bf16 v[130:133], v[160:163], v[178:181], v[130:133]
	v_mfma_f32_16x16x32_bf16 v[58:61], v[170:173], v[178:181], v[58:61]
	v_mfma_f32_16x16x32_bf16 v[122:125], v[160:163], v[186:189], v[122:125]
	v_mfma_f32_16x16x32_bf16 v[50:53], v[170:173], v[186:189], v[50:53]
	v_mfma_f32_16x16x32_bf16 v[114:117], v[160:163], v[202:205], v[114:117]
	v_mfma_f32_16x16x32_bf16 v[42:45], v[170:173], v[202:205], v[42:45]
	v_mfma_f32_16x16x32_bf16 v[106:109], v[160:163], v[210:213], v[106:109]
	v_mfma_f32_16x16x32_bf16 v[34:37], v[170:173], v[210:213], v[34:37]
	s_setprio 0
	s_barrier
; #define PG8_STAGE(bufoff, gbase, voff) do { _Pragma("unroll") for (int _i = 0; _i < 2; ++_i) \
;         __builtin_amdgcn_global_load_lds((const unsigned*)((const char*)(gbase) + (voff)[_i]), (LAS unsigned*)(lds + (bufoff) + ldsw + _i * 8192), 16, 0, 0); } while (0)
; #define PG8_LDA(dst, b, h) do { _Pragma("unroll") for (int m = 0; m < 4; ++m) _Pragma("unroll") for (int k = 0; k < 2; ++k) dst[m][k] = *(const LAS bf16x8*)(lds + PG8_SA(b, h) + aoff + m * 2048 + k * 1024); } while (0)
; #define PG8_MMA(ai, bj, At, Bt) do { __builtin_amdgcn_s_setprio(1); _Pragma("unroll") for (int m = 0; m < 4; ++m) _Pragma("unroll") for (int n = 0; n < 2; ++n) _Pragma("unroll") for (int k = 0; k < 2; ++k) \
;         acc[ai][bj][m][n] = __builtin_amdgcn_mfma_f32_16x16x32_bf16(Bt[n][k], At[m][k], acc[ai][bj][m][n], 0, 0, 0); __builtin_amdgcn_s_setprio(0); } while (0)
; #define PG8_WAIT_V(n) asm volatile("s_waitcnt vmcnt(" #n ")" ::: "memory")
; #define PG8_WAIT_L(n) asm volatile("s_waitcnt lgkmcnt(" #n ")" ::: "memory")
; #define PG8_BAR __builtin_amdgcn_s_barrier()
; #define PG8_SCHED __builtin_amdgcn_sched_barrier(0)
; template <class Epi>
; __device__ __forceinline__ void gemm_phase(LAS unsigned char* lds, const Gemm g, const StaticOrder& S, const Epi& E, const int tid) {
;     ...
;             PG8_LDA(At, 0, 1); PG8_STAGE(PG8_SB(0, 0), b2, voffB); PG8_STAGE(PG8_SB(0, 1), b2 + hstepB, voffB); PG8_STAGE(PG8_SA(0, 0), a2, voffA);
;             PG8_WAIT_V(8); PG8_WAIT_L(0); PG8_BAR; PG8_MMA(1, 0, At, B0); PG8_MMA(1, 1, At, B1); PG8_BAR; PG8_SCHED;
	s_add_i32 s62, s62, s3
	v_lshl_add_u64 v[194:195], s[60:61], 0, v[0:1]
	s_mov_b32 m0, s62
	ds_read_b128 v[174:177], v169 offset:16384
	ds_read_b128 v[178:181], v169 offset:17408
	ds_read_b128 v[182:185], v169 offset:18432
	ds_read_b128 v[186:189], v169 offset:19456
	ds_read_b128 v[190:193], v169 offset:20480
	ds_read_b128 v[202:205], v169 offset:21504
	ds_read_b128 v[206:209], v169 offset:22528
	ds_read_b128 v[210:213], v169 offset:23552
	global_load_lds_dwordx4 v[194:195], off
	s_add_i32 m0, s62, 0x2000
	v_lshl_add_u64 v[196:197], s[60:61], 0, v[146:147]
	s_add_u32 s60, s60, s12
	s_addc_u32 s61, s61, s13
	s_add_i32 s39, s39, s3
	global_load_lds_dwordx4 v[196:197], off
	v_lshl_add_u64 v[198:199], s[60:61], 0, v[0:1]
	s_mov_b32 m0, s39
	v_lshl_add_u64 v[214:215], s[60:61], 0, v[146:147]
	global_load_lds_dwordx4 v[198:199], off
	s_add_i32 m0, s39, 0x2000
	v_lshl_add_u64 v[216:217], s[36:37], 0, v[142:143]
	global_load_lds_dwordx4 v[214:215], off
	s_mov_b32 m0, s44
	v_lshl_add_u64 v[218:219], s[36:37], 0, v[144:145]
	global_load_lds_dwordx4 v[216:217], off
	s_mov_b32 m0, s45
	s_nop 0
	global_load_lds_dwordx4 v[218:219], off
	s_waitcnt vmcnt(8)
	s_waitcnt lgkmcnt(0)
	s_barrier
	s_setprio 1
	s_waitcnt lgkmcnt(0)
	v_mfma_f32_16x16x32_bf16 v[102:105], v[82:85], v[174:177], 0
	v_mfma_f32_16x16x32_bf16 v[30:33], v[138:141], v[174:177], 0
	v_mfma_f32_16x16x32_bf16 v[94:97], v[82:85], v[182:185], 0
	v_mfma_f32_16x16x32_bf16 v[22:25], v[138:141], v[182:185], 0
	v_mfma_f32_16x16x32_bf16 v[78:81], v[82:85], v[190:193], 0
	v_mfma_f32_16x16x32_bf16 v[14:17], v[138:141], v[190:193], 0
	v_mfma_f32_16x16x32_bf16 v[70:73], v[82:85], v[206:209], 0
	v_mfma_f32_16x16x32_bf16 v[6:9], v[138:141], v[206:209], 0
	v_mfma_f32_16x16x32_bf16 v[102:105], v[86:89], v[178:181], v[102:105]
	v_mfma_f32_16x16x32_bf16 v[30:33], v[152:155], v[178:181], v[30:33]
	v_mfma_f32_16x16x32_bf16 v[94:97], v[86:89], v[186:189], v[94:97]
	v_mfma_f32_16x16x32_bf16 v[22:25], v[152:155], v[186:189], v[22:25]
	v_mfma_f32_16x16x32_bf16 v[78:81], v[86:89], v[202:205], v[78:81]
	v_mfma_f32_16x16x32_bf16 v[14:17], v[152:155], v[202:205], v[14:17]
	v_mfma_f32_16x16x32_bf16 v[70:73], v[86:89], v[210:213], v[70:73]
	v_mfma_f32_16x16x32_bf16 v[6:9], v[152:155], v[210:213], v[6:9]
	s_setprio 0
	s_setprio 1
	v_mfma_f32_16x16x32_bf16 v[26:29], v[164:167], v[174:177], 0
	v_mfma_f32_16x16x32_bf16 v[18:21], v[164:167], v[182:185], 0
	v_mfma_f32_16x16x32_bf16 v[74:77], v[156:159], v[190:193], 0
	v_mfma_f32_16x16x32_bf16 v[10:13], v[164:167], v[190:193], 0
	v_mfma_f32_16x16x32_bf16 v[66:69], v[156:159], v[206:209], 0
	v_mfma_f32_16x16x32_bf16 v[2:5], v[164:167], v[206:209], 0
	v_mfma_f32_16x16x32_bf16 v[82:85], v[156:159], v[174:177], 0
	v_mfma_f32_16x16x32_bf16 v[26:29], v[170:173], v[178:181], v[26:29]
	v_mfma_f32_16x16x32_bf16 v[86:89], v[156:159], v[182:185], 0
	v_mfma_f32_16x16x32_bf16 v[18:21], v[170:173], v[186:189], v[18:21]
	v_mfma_f32_16x16x32_bf16 v[74:77], v[160:163], v[202:205], v[74:77]
	v_mfma_f32_16x16x32_bf16 v[10:13], v[170:173], v[202:205], v[10:13]
	v_mfma_f32_16x16x32_bf16 v[66:69], v[160:163], v[210:213], v[66:69]
	v_mfma_f32_16x16x32_bf16 v[2:5], v[170:173], v[210:213], v[2:5]
	v_mfma_f32_16x16x32_bf16 v[82:85], v[160:163], v[178:181], v[82:85]
	v_mfma_f32_16x16x32_bf16 v[86:89], v[160:163], v[186:189], v[86:89]
	s_setprio 0
	s_barrier
	s_branch .Lkl185_sp2

; #define PG8_STAGE(bufoff, gbase, voff) do { _Pragma("unroll") for (int _i = 0; _i < 2; ++_i) \
;         __builtin_amdgcn_global_load_lds((const unsigned*)((const char*)(gbase) + (voff)[_i]), (LAS unsigned*)(lds + (bufoff) + ldsw + _i * 8192), 16, 0, 0); } while (0)
; #define PG8_LDA(dst, b, h) do { _Pragma("unroll") for (int m = 0; m < 4; ++m) _Pragma("unroll") for (int k = 0; k < 2; ++k) dst[m][k] = *(const LAS bf16x8*)(lds + PG8_SA(b, h) + aoff + m * 2048 + k * 1024); } while (0)
; #define PG8_LDB(dst, b, h) do { _Pragma("unroll") for (int n = 0; n < 2; ++n) _Pragma("unroll") for (int k = 0; k < 2; ++k) dst[n][k] = *(const LAS bf16x8*)(lds + PG8_SB(b, h) + boff + n * 2048 + k * 1024); } while (0)
; #define PG8_MMA(ai, bj, At, Bt) do { __builtin_amdgcn_s_setprio(1); _Pragma("unroll") for (int m = 0; m < 4; ++m) _Pragma("unroll") for (int n = 0; n < 2; ++n) _Pragma("unroll") for (int k = 0; k < 2; ++k) \
;         acc[ai][bj][m][n] = __builtin_amdgcn_mfma_f32_16x16x32_bf16(Bt[n][k], At[m][k], acc[ai][bj][m][n], 0, 0, 0); __builtin_amdgcn_s_setprio(0); } while (0)
; #define PG8_WAIT_V(n) asm volatile("s_waitcnt vmcnt(" #n ")" ::: "memory")
; #define PG8_WAIT_L(n) asm volatile("s_waitcnt lgkmcnt(" #n ")" ::: "memory")
; #define PG8_BAR __builtin_amdgcn_s_barrier()
; #define PG8_SCHED __builtin_amdgcn_sched_barrier(0)
; template <class Epi>
; __device__ __forceinline__ void gemm_phase(LAS unsigned char* lds, const Gemm g, const StaticOrder& S, const Epi& E, const int tid) {
;     ...
;             PG8_LDB(B0, 1, 0); PG8_LDB(B1, 1, 1); PG8_SCHED; PG8_LDA(At, 1, 0); PG8_STAGE(PG8_SA(0, 1), a2 + hstepA, voffA);
;             PG8_WAIT_V(8); PG8_WAIT_L(0); PG8_BAR; PG8_MMA(0, 0, At, B0); PG8_MMA(0, 1, At, B1); PG8_BAR; PG8_SCHED;
.Lkl185_sp2:
	s_add_i32 s39, 0, 0x18000
	s_add_i32 s60, 0, 0x1c000
	v_add_u32_e32 v152, s39, v168
	v_add_u32_e32 v170, s60, v168
	ds_read_b128 v[90:93], v152
	ds_read_b128 v[98:101], v152 offset:1024
	ds_read_b128 v[138:141], v152 offset:2048
	ds_read_b128 v[152:155], v152 offset:3072
	ds_read_b128 v[156:159], v170
	ds_read_b128 v[160:163], v170 offset:1024
	ds_read_b128 v[164:167], v170 offset:2048
	ds_read_b128 v[170:173], v170 offset:3072
	s_add_u32 s36, s36, s10
	s_addc_u32 s37, s37, s11
	s_mov_b32 m0, s46
	v_lshl_add_u64 v[220:221], s[36:37], 0, v[142:143]
	ds_read_b128 v[174:177], v169 offset:32768
	ds_read_b128 v[178:181], v169 offset:33792
	ds_read_b128 v[182:185], v169 offset:34816
	ds_read_b128 v[186:189], v169 offset:35840
	ds_read_b128 v[190:193], v169 offset:36864
	ds_read_b128 v[202:205], v169 offset:37888
	ds_read_b128 v[206:209], v169 offset:38912
	ds_read_b128 v[210:213], v169 offset:39936
	global_load_lds_dwordx4 v[220:221], off
	v_lshl_add_u64 v[220:221], s[36:37], 0, v[144:145]
	s_mov_b32 m0, s47
	s_nop 0
	global_load_lds_dwordx4 v[220:221], off
	s_waitcnt vmcnt(8)
	s_waitcnt lgkmcnt(0)
	s_barrier
	s_setprio 1
	s_waitcnt lgkmcnt(0)
	v_mfma_f32_16x16x32_bf16 v[134:137], v[90:93], v[174:177], v[134:137]
	v_mfma_f32_16x16x32_bf16 v[62:65], v[138:141], v[174:177], v[62:65]
	v_mfma_f32_16x16x32_bf16 v[126:129], v[90:93], v[182:185], v[126:129]
	v_mfma_f32_16x16x32_bf16 v[54:57], v[138:141], v[182:185], v[54:57]
	v_mfma_f32_16x16x32_bf16 v[118:121], v[90:93], v[190:193], v[118:121]
	v_mfma_f32_16x16x32_bf16 v[46:49], v[138:141], v[190:193], v[46:49]
	v_mfma_f32_16x16x32_bf16 v[110:113], v[90:93], v[206:209], v[110:113]
	v_mfma_f32_16x16x32_bf16 v[38:41], v[138:141], v[206:209], v[38:41]
	v_mfma_f32_16x16x32_bf16 v[134:137], v[98:101], v[178:181], v[134:137]
	v_mfma_f32_16x16x32_bf16 v[62:65], v[152:155], v[178:181], v[62:65]
	v_mfma_f32_16x16x32_bf16 v[126:129], v[98:101], v[186:189], v[126:129]
	v_mfma_f32_16x16x32_bf16 v[54:57], v[152:155], v[186:189], v[54:57]
	v_mfma_f32_16x16x32_bf16 v[118:121], v[98:101], v[202:205], v[118:121]
	v_mfma_f32_16x16x32_bf16 v[46:49], v[152:155], v[202:205], v[46:49]
	v_mfma_f32_16x16x32_bf16 v[110:113], v[98:101], v[210:213], v[110:113]
	v_mfma_f32_16x16x32_bf16 v[38:41], v[152:155], v[210:213], v[38:41]
	s_setprio 0
	s_setprio 1
	v_mfma_f32_16x16x32_bf16 v[130:133], v[156:159], v[174:177], v[130:133]
	v_mfma_f32_16x16x32_bf16 v[58:61], v[164:167], v[174:177], v[58:61]
	v_mfma_f32_16x16x32_bf16 v[122:125], v[156:159], v[182:185], v[122:125]
	v_mfma_f32_16x16x32_bf16 v[50:53], v[164:167], v[182:185], v[50:53]
	v_mfma_f32_16x16x32_bf16 v[114:117], v[156:159], v[190:193], v[114:117]
	v_mfma_f32_16x16x32_bf16 v[42:45], v[164:167], v[190:193], v[42:45]
	v_mfma_f32_16x16x32_bf16 v[106:109], v[156:159], v[206:209], v[106:109]
	v_mfma_f32_16x16x32_bf16 v[34:37], v[164:167], v[206:209], v[34:37]
	v_mfma_f32_16x16x32_bf16 v[130:133], v[160:163], v[178:181], v[130:133]
	v_mfma_f32_16x16x32_bf16 v[58:61], v[170:173], v[178:181], v[58:61]
	v_mfma_f32_16x16x32_bf16 v[122:125], v[160:163], v[186:189], v[122:125]
	v_mfma_f32_16x16x32_bf16 v[50:53], v[170:173], v[186:189], v[50:53]
	v_mfma_f32_16x16x32_bf16 v[114:117], v[160:163], v[202:205], v[114:117]
	v_mfma_f32_16x16x32_bf16 v[42:45], v[170:173], v[202:205], v[42:45]
	v_mfma_f32_16x16x32_bf16 v[106:109], v[160:163], v[210:213], v[106:109]
	v_mfma_f32_16x16x32_bf16 v[34:37], v[170:173], v[210:213], v[34:37]
	s_setprio 0
	s_barrier
; #define PG8_STAGE(bufoff, gbase, voff) do { _Pragma("unroll") for (int _i = 0; _i < 2; ++_i) \
;         __builtin_amdgcn_global_load_lds((const unsigned*)((const char*)(gbase) + (voff)[_i]), (LAS unsigned*)(lds + (bufoff) + ldsw + _i * 8192), 16, 0, 0); } while (0)
; #define PG8_LDA(dst, b, h) do { _Pragma("unroll") for (int m = 0; m < 4; ++m) _Pragma("unroll") for (int k = 0; k < 2; ++k) dst[m][k] = *(const LAS bf16x8*)(lds + PG8_SA(b, h) + aoff + m * 2048 + k * 1024); } while (0)
; #define PG8_MMA(ai, bj, At, Bt) do { __builtin_amdgcn_s_setprio(1); _Pragma("unroll") for (int m = 0; m < 4; ++m) _Pragma("unroll") for (int n = 0; n < 2; ++n) _Pragma("unroll") for (int k = 0; k < 2; ++k) \
;         acc[ai][bj][m][n] = __builtin_amdgcn_mfma_f32_16x16x32_bf16(Bt[n][k], At[m][k], acc[ai][bj][m][n], 0, 0, 0); __builtin_amdgcn_s_setprio(0); } while (0)
; #define PG8_WAIT_V(n) asm volatile("s_waitcnt vmcnt(" #n ")" ::: "memory")
; #define PG8_WAIT_L(n) asm volatile("s_waitcnt lgkmcnt(" #n ")" ::: "memory")
; #define PG8_BAR __builtin_amdgcn_s_barrier()
; #define PG8_SCHED __builtin_amdgcn_sched_barrier(0)
; template <class Epi>
; __device__ __forceinline__ void gemm_phase(LAS unsigned char* lds, const Gemm g, const StaticOrder& S, const Epi& E, const int tid) {
;     ...
;             PG8_LDA(At, 1, 1); PG8_STAGE(PG8_SB(1, 0), b3, voffB); PG8_STAGE(PG8_SB(1, 1), b3 + hstepB, voffB); PG8_STAGE(PG8_SA(1, 0), a3, voffA);
;             PG8_WAIT_V(8); PG8_WAIT_L(0); PG8_BAR; PG8_MMA(1, 0, At, B0); PG8_MMA(1, 1, At, B1); PG8_BAR; PG8_SCHED;
	s_add_i32 s36, s39, s3
	v_lshl_add_u64 v[194:195], v[194:195], 0, s[80:81]
	s_mov_b32 m0, s36
	ds_read_b128 v[174:177], v169 offset:49152
	ds_read_b128 v[178:181], v169 offset:50176
	ds_read_b128 v[182:185], v169 offset:51200
	ds_read_b128 v[186:189], v169 offset:52224
	ds_read_b128 v[190:193], v169 offset:53248
	ds_read_b128 v[202:205], v169 offset:54272
	ds_read_b128 v[206:209], v169 offset:55296
	ds_read_b128 v[210:213], v169 offset:56320
	global_load_lds_dwordx4 v[194:195], off
	v_lshl_add_u64 v[194:195], v[196:197], 0, s[80:81]
	s_add_i32 m0, s36, 0x2000
	s_add_i32 s36, s60, s3
	global_load_lds_dwordx4 v[194:195], off
	v_lshl_add_u64 v[194:195], v[198:199], 0, s[80:81]
	s_mov_b32 m0, s36
	s_nop 0
	global_load_lds_dwordx4 v[194:195], off
	v_lshl_add_u64 v[194:195], v[214:215], 0, s[80:81]
	s_add_i32 m0, s36, 0x2000
	s_nop 0
	global_load_lds_dwordx4 v[194:195], off
	v_lshl_add_u64 v[194:195], v[216:217], 0, s[80:81]
	s_mov_b32 m0, s51
	s_nop 0
	global_load_lds_dwordx4 v[194:195], off
	v_lshl_add_u64 v[194:195], v[218:219], 0, s[80:81]
	s_mov_b32 m0, s52
	s_nop 0
	global_load_lds_dwordx4 v[194:195], off
	s_waitcnt vmcnt(8)
	s_waitcnt lgkmcnt(0)
	s_nop 0
	s_barrier
	s_setprio 1
	s_waitcnt lgkmcnt(0)
	v_mfma_f32_16x16x32_bf16 v[102:105], v[90:93], v[174:177], v[102:105]
	v_mfma_f32_16x16x32_bf16 v[30:33], v[138:141], v[174:177], v[30:33]
	v_mfma_f32_16x16x32_bf16 v[94:97], v[90:93], v[182:185], v[94:97]
	v_mfma_f32_16x16x32_bf16 v[22:25], v[138:141], v[182:185], v[22:25]
	v_mfma_f32_16x16x32_bf16 v[78:81], v[90:93], v[190:193], v[78:81]
	v_mfma_f32_16x16x32_bf16 v[14:17], v[138:141], v[190:193], v[14:17]
	v_mfma_f32_16x16x32_bf16 v[70:73], v[90:93], v[206:209], v[70:73]
	v_mfma_f32_16x16x32_bf16 v[6:9], v[138:141], v[206:209], v[6:9]
	v_mfma_f32_16x16x32_bf16 v[102:105], v[98:101], v[178:181], v[102:105]
	v_mfma_f32_16x16x32_bf16 v[30:33], v[152:155], v[178:181], v[30:33]
	v_mfma_f32_16x16x32_bf16 v[94:97], v[98:101], v[186:189], v[94:97]
	v_mfma_f32_16x16x32_bf16 v[22:25], v[152:155], v[186:189], v[22:25]
	v_mfma_f32_16x16x32_bf16 v[78:81], v[98:101], v[202:205], v[78:81]
	v_mfma_f32_16x16x32_bf16 v[14:17], v[152:155], v[202:205], v[14:17]
	v_mfma_f32_16x16x32_bf16 v[70:73], v[98:101], v[210:213], v[70:73]
	v_mfma_f32_16x16x32_bf16 v[6:9], v[152:155], v[210:213], v[6:9]
	s_setprio 0
	s_setprio 1
	v_mfma_f32_16x16x32_bf16 v[82:85], v[156:159], v[174:177], v[82:85]
	v_mfma_f32_16x16x32_bf16 v[98:101], v[160:163], v[178:181], v[82:85]
	v_mfma_f32_16x16x32_bf16 v[26:29], v[164:167], v[174:177], v[26:29]
	v_mfma_f32_16x16x32_bf16 v[82:85], v[156:159], v[182:185], v[86:89]
	v_mfma_f32_16x16x32_bf16 v[18:21], v[164:167], v[182:185], v[18:21]
	v_mfma_f32_16x16x32_bf16 v[74:77], v[156:159], v[190:193], v[74:77]
	v_mfma_f32_16x16x32_bf16 v[10:13], v[164:167], v[190:193], v[10:13]
	v_mfma_f32_16x16x32_bf16 v[66:69], v[156:159], v[206:209], v[66:69]
	v_mfma_f32_16x16x32_bf16 v[2:5], v[164:167], v[206:209], v[2:5]
	v_mfma_f32_16x16x32_bf16 v[26:29], v[170:173], v[178:181], v[26:29]
	v_mfma_f32_16x16x32_bf16 v[90:93], v[160:163], v[186:189], v[82:85]
	v_mfma_f32_16x16x32_bf16 v[18:21], v[170:173], v[186:189], v[18:21]
	v_mfma_f32_16x16x32_bf16 v[74:77], v[160:163], v[202:205], v[74:77]
	v_mfma_f32_16x16x32_bf16 v[10:13], v[170:173], v[202:205], v[10:13]
	v_mfma_f32_16x16x32_bf16 v[66:69], v[160:163], v[210:213], v[66:69]
	v_mfma_f32_16x16x32_bf16 v[2:5], v[170:173], v[210:213], v[2:5]
	s_setprio 0
	s_barrier
	s_add_u32 s0, s0, 0x100
	s_addc_u32 s1, s1, 0
	s_add_u32 s6, s6, 0x100
	s_addc_u32 s7, s7, 0
	s_cmp_ge_i32 s38, s48
	s_mov_b32 s36, s38
	s_cbranch_scc0 .LBB0_185
	s_movk_i32 s61, 0xf000
	s_mov_b32 s60, 0x800000

; #define PG8_STAGE(bufoff, gbase, voff) do { _Pragma("unroll") for (int _i = 0; _i < 2; ++_i) \
;         __builtin_amdgcn_global_load_lds((const unsigned*)((const char*)(gbase) + (voff)[_i]), (LAS unsigned*)(lds + (bufoff) + ldsw + _i * 8192), 16, 0, 0); } while (0)
; #define PG8_LDA(dst, b, h) do { _Pragma("unroll") for (int m = 0; m < 4; ++m) _Pragma("unroll") for (int k = 0; k < 2; ++k) dst[m][k] = *(const LAS bf16x8*)(lds + PG8_SA(b, h) + aoff + m * 2048 + k * 1024); } while (0)
; #define PG8_LDB(dst, b, h) do { _Pragma("unroll") for (int n = 0; n < 2; ++n) _Pragma("unroll") for (int k = 0; k < 2; ++k) dst[n][k] = *(const LAS bf16x8*)(lds + PG8_SB(b, h) + boff + n * 2048 + k * 1024); } while (0)
; #define PG8_MMA(ai, bj, At, Bt) do { __builtin_amdgcn_s_setprio(1); _Pragma("unroll") for (int m = 0; m < 4; ++m) _Pragma("unroll") for (int n = 0; n < 2; ++n) _Pragma("unroll") for (int k = 0; k < 2; ++k) \
;         acc[ai][bj][m][n] = __builtin_amdgcn_mfma_f32_16x16x32_bf16(Bt[n][k], At[m][k], acc[ai][bj][m][n], 0, 0, 0); __builtin_amdgcn_s_setprio(0); } while (0)
; #define PG8_WAIT_V(n) asm volatile("s_waitcnt vmcnt(" #n ")" ::: "memory")
; #define PG8_WAIT_L(n) asm volatile("s_waitcnt lgkmcnt(" #n ")" ::: "memory")
; #define PG8_BAR __builtin_amdgcn_s_barrier()
; #define PG8_SCHED __builtin_amdgcn_sched_barrier(0)
; template <class Epi>
; __device__ __forceinline__ void gemm_phase(LAS unsigned char* lds, const Gemm g, const StaticOrder& S, const Epi& E, const int tid) {
;     ...
;             PG8_LDB(B0, 0, 0); PG8_LDB(B1, 0, 1); PG8_SCHED; PG8_LDA(At, 0, 0); PG8_STAGE(PG8_SA(1, 1), a1 + hstepA, voffA);
;             PG8_WAIT_V(8); PG8_WAIT_L(0); PG8_BAR; PG8_MMA(0, 0, At, B0); PG8_MMA(0, 1, At, B1); PG8_BAR; PG8_SCHED;
;             PG8_LDA(At, 0, 1); PG8_STAGE(PG8_SB(0, 0), b2, voffB); PG8_STAGE(PG8_SB(0, 1), b2 + hstepB, voffB); PG8_STAGE(PG8_SA(0, 0), a2, voffA);
.Lkl298_nofa:
	s_waitcnt vmcnt(18)
	s_waitcnt lgkmcnt(0)
	s_nop 0
	s_barrier
	s_setprio 1
	s_waitcnt lgkmcnt(0)
	v_mfma_f32_16x16x32_bf16 v[122:125], v[130:133], v[162:165], 0
	v_mfma_f32_16x16x32_bf16 v[126:129], v[138:141], v[162:165], 0
	v_mfma_f32_16x16x32_bf16 v[110:113], v[130:133], v[170:173], 0
	v_mfma_f32_16x16x32_bf16 v[106:109], v[138:141], v[170:173], 0
	v_mfma_f32_16x16x32_bf16 v[94:97], v[130:133], v[178:181], 0
	v_mfma_f32_16x16x32_bf16 v[90:93], v[138:141], v[178:181], 0
	v_mfma_f32_16x16x32_bf16 v[78:81], v[130:133], v[186:189], 0
	v_mfma_f32_16x16x32_bf16 v[74:77], v[138:141], v[186:189], 0
	v_mfma_f32_16x16x32_bf16 v[122:125], v[134:137], v[166:169], v[122:125]
	v_mfma_f32_16x16x32_bf16 v[126:129], v[142:145], v[166:169], v[126:129]
	v_mfma_f32_16x16x32_bf16 v[110:113], v[134:137], v[174:177], v[110:113]
	v_mfma_f32_16x16x32_bf16 v[106:109], v[142:145], v[174:177], v[106:109]
	v_mfma_f32_16x16x32_bf16 v[94:97], v[134:137], v[182:185], v[94:97]
	v_mfma_f32_16x16x32_bf16 v[90:93], v[142:145], v[182:185], v[90:93]
	v_mfma_f32_16x16x32_bf16 v[78:81], v[134:137], v[190:193], v[78:81]
	v_mfma_f32_16x16x32_bf16 v[74:77], v[142:145], v[190:193], v[74:77]
	s_setprio 0
	s_setprio 1
	v_mfma_f32_16x16x32_bf16 v[118:121], v[146:149], v[162:165], 0
	v_mfma_f32_16x16x32_bf16 v[114:117], v[154:157], v[162:165], 0
	v_mfma_f32_16x16x32_bf16 v[102:105], v[146:149], v[170:173], 0
	v_mfma_f32_16x16x32_bf16 v[98:101], v[154:157], v[170:173], 0
	v_mfma_f32_16x16x32_bf16 v[86:89], v[146:149], v[178:181], 0
	v_mfma_f32_16x16x32_bf16 v[82:85], v[154:157], v[178:181], 0
	v_mfma_f32_16x16x32_bf16 v[70:73], v[146:149], v[186:189], 0
	v_mfma_f32_16x16x32_bf16 v[66:69], v[154:157], v[186:189], 0
	v_mfma_f32_16x16x32_bf16 v[118:121], v[150:153], v[166:169], v[118:121]
	v_mfma_f32_16x16x32_bf16 v[114:117], v[158:161], v[166:169], v[114:117]
	v_mfma_f32_16x16x32_bf16 v[102:105], v[150:153], v[174:177], v[102:105]
	v_mfma_f32_16x16x32_bf16 v[98:101], v[158:161], v[174:177], v[98:101]
	v_mfma_f32_16x16x32_bf16 v[86:89], v[150:153], v[182:185], v[86:89]
	v_mfma_f32_16x16x32_bf16 v[82:85], v[158:161], v[182:185], v[82:85]
	v_mfma_f32_16x16x32_bf16 v[70:73], v[150:153], v[190:193], v[70:73]
	v_mfma_f32_16x16x32_bf16 v[66:69], v[158:161], v[190:193], v[66:69]
	s_setprio 0
	s_barrier
	s_add_i32 s60, s60, s11
	v_lshl_add_u64 v[212:213], s[58:59], 0, v[0:1]
	s_mov_b32 m0, s60
	ds_read_b128 v[162:165], v194 offset:16384
	ds_read_b128 v[166:169], v194 offset:17408
	ds_read_b128 v[170:173], v194 offset:18432
	ds_read_b128 v[174:177], v194 offset:19456
	ds_read_b128 v[178:181], v194 offset:20480
	ds_read_b128 v[182:185], v194 offset:21504
	ds_read_b128 v[186:189], v194 offset:22528
	ds_read_b128 v[190:193], v194 offset:23552
	global_load_lds_dwordx4 v[212:213], off
	s_add_i32 m0, s60, 0x2000
	v_lshl_add_u64 v[214:215], s[58:59], 0, v[206:207]
	s_add_u32 s58, s58, s14
	s_addc_u32 s59, s59, s15
	s_add_i32 s37, s37, s11
	global_load_lds_dwordx4 v[214:215], off
	v_lshl_add_u64 v[216:217], s[58:59], 0, v[0:1]
	s_mov_b32 m0, s37
	v_lshl_add_u64 v[218:219], s[58:59], 0, v[206:207]
	global_load_lds_dwordx4 v[216:217], off
	s_add_i32 m0, s37, 0x2000
	v_lshl_add_u64 v[220:221], s[34:35], 0, v[202:203]
	global_load_lds_dwordx4 v[218:219], off
	s_mov_b32 m0, s38
	v_lshl_add_u64 v[222:223], s[34:35], 0, v[204:205]
	global_load_lds_dwordx4 v[220:221], off
	s_mov_b32 m0, s39
	s_nop 0
	global_load_lds_dwordx4 v[222:223], off
	s_cmp_eq_u32 s53, 1
	s_cbranch_scc1 .Lkl298_w1f
	s_waitcnt vmcnt(24)
	s_branch .Lkl298_w1j

; #define PG8_STAGE(bufoff, gbase, voff) do { _Pragma("unroll") for (int _i = 0; _i < 2; ++_i) \
;         __builtin_amdgcn_global_load_lds((const unsigned*)((const char*)(gbase) + (voff)[_i]), (LAS unsigned*)(lds + (bufoff) + ldsw + _i * 8192), 16, 0, 0); } while (0)
; #define PG8_LDA(dst, b, h) do { _Pragma("unroll") for (int m = 0; m < 4; ++m) _Pragma("unroll") for (int k = 0; k < 2; ++k) dst[m][k] = *(const LAS bf16x8*)(lds + PG8_SA(b, h) + aoff + m * 2048 + k * 1024); } while (0)
; #define PG8_MMA(ai, bj, At, Bt) do { __builtin_amdgcn_s_setprio(1); _Pragma("unroll") for (int m = 0; m < 4; ++m) _Pragma("unroll") for (int n = 0; n < 2; ++n) _Pragma("unroll") for (int k = 0; k < 2; ++k) \
;         acc[ai][bj][m][n] = __builtin_amdgcn_mfma_f32_16x16x32_bf16(Bt[n][k], At[m][k], acc[ai][bj][m][n], 0, 0, 0); __builtin_amdgcn_s_setprio(0); } while (0)
; #define PG8_WAIT_V(n) asm volatile("s_waitcnt vmcnt(" #n ")" ::: "memory")
; #define PG8_WAIT_L(n) asm volatile("s_waitcnt lgkmcnt(" #n ")" ::: "memory")
; #define PG8_BAR __builtin_amdgcn_s_barrier()
; #define PG8_SCHED __builtin_amdgcn_sched_barrier(0)
; template <class Epi>
; __device__ __forceinline__ void gemm_phase(LAS unsigned char* lds, const Gemm g, const StaticOrder& S, const Epi& E, const int tid) {
;     ...
;             PG8_LDA(At, 1, 1); PG8_STAGE(PG8_SB(1, 0), b3, voffB); PG8_STAGE(PG8_SB(1, 1), b3 + hstepB, voffB); PG8_STAGE(PG8_SA(1, 0), a3, voffA);
;             PG8_WAIT_V(8); PG8_WAIT_L(0); PG8_BAR; PG8_MMA(1, 0, At, B0); PG8_MMA(1, 1, At, B1); PG8_BAR; PG8_SCHED;
.Lkl298_sp3:
	s_add_i32 s34, s37, s11
	v_lshl_add_u64 v[212:213], v[212:213], 0, s[80:81]
	s_mov_b32 m0, s34
	ds_read_b128 v[162:165], v194 offset:49152
	ds_read_b128 v[166:169], v194 offset:50176
	ds_read_b128 v[170:173], v194 offset:51200
	ds_read_b128 v[174:177], v194 offset:52224
	ds_read_b128 v[178:181], v194 offset:53248
	ds_read_b128 v[182:185], v194 offset:54272
	ds_read_b128 v[186:189], v194 offset:55296
	ds_read_b128 v[190:193], v194 offset:56320
	global_load_lds_dwordx4 v[212:213], off
	v_lshl_add_u64 v[212:213], v[214:215], 0, s[80:81]
	s_add_i32 m0, s34, 0x2000
	s_add_i32 s34, s58, s11
	global_load_lds_dwordx4 v[212:213], off
	v_lshl_add_u64 v[212:213], v[216:217], 0, s[80:81]
	s_mov_b32 m0, s34
	s_nop 0
	global_load_lds_dwordx4 v[212:213], off
	v_lshl_add_u64 v[212:213], v[218:219], 0, s[80:81]
	s_add_i32 m0, s34, 0x2000
	s_nop 0
	global_load_lds_dwordx4 v[212:213], off
	v_lshl_add_u64 v[212:213], v[220:221], 0, s[80:81]
	s_mov_b32 m0, s49
	s_nop 0
	global_load_lds_dwordx4 v[212:213], off
	v_lshl_add_u64 v[212:213], v[222:223], 0, s[80:81]
	s_mov_b32 m0, s50
	s_nop 0
	global_load_lds_dwordx4 v[212:213], off
	s_waitcnt vmcnt(8)
	s_waitcnt lgkmcnt(0)
	s_nop 0
	s_barrier
	s_setprio 1
	s_waitcnt lgkmcnt(0)
	v_mfma_f32_16x16x32_bf16 v[62:65], v[130:133], v[162:165], v[62:65]
	v_mfma_f32_16x16x32_bf16 v[58:61], v[138:141], v[162:165], v[58:61]
	v_mfma_f32_16x16x32_bf16 v[46:49], v[130:133], v[170:173], v[46:49]
	v_mfma_f32_16x16x32_bf16 v[42:45], v[138:141], v[170:173], v[42:45]
	v_mfma_f32_16x16x32_bf16 v[30:33], v[130:133], v[178:181], v[30:33]
	v_mfma_f32_16x16x32_bf16 v[26:29], v[138:141], v[178:181], v[26:29]
	v_mfma_f32_16x16x32_bf16 v[14:17], v[130:133], v[186:189], v[14:17]
	v_mfma_f32_16x16x32_bf16 v[10:13], v[138:141], v[186:189], v[10:13]
	v_mfma_f32_16x16x32_bf16 v[62:65], v[134:137], v[166:169], v[62:65]
	v_mfma_f32_16x16x32_bf16 v[58:61], v[142:145], v[166:169], v[58:61]
	v_mfma_f32_16x16x32_bf16 v[46:49], v[134:137], v[174:177], v[46:49]
	v_mfma_f32_16x16x32_bf16 v[42:45], v[142:145], v[174:177], v[42:45]
	v_mfma_f32_16x16x32_bf16 v[30:33], v[134:137], v[182:185], v[30:33]
	v_mfma_f32_16x16x32_bf16 v[26:29], v[142:145], v[182:185], v[26:29]
	v_mfma_f32_16x16x32_bf16 v[14:17], v[134:137], v[190:193], v[14:17]
	v_mfma_f32_16x16x32_bf16 v[10:13], v[142:145], v[190:193], v[10:13]
	s_setprio 0
	s_setprio 1
	v_mfma_f32_16x16x32_bf16 v[54:57], v[146:149], v[162:165], v[54:57]
	v_mfma_f32_16x16x32_bf16 v[50:53], v[154:157], v[162:165], v[50:53]
	v_mfma_f32_16x16x32_bf16 v[38:41], v[146:149], v[170:173], v[38:41]
	v_mfma_f32_16x16x32_bf16 v[34:37], v[154:157], v[170:173], v[34:37]
	v_mfma_f32_16x16x32_bf16 v[22:25], v[146:149], v[178:181], v[22:25]
	v_mfma_f32_16x16x32_bf16 v[18:21], v[154:157], v[178:181], v[18:21]
	v_mfma_f32_16x16x32_bf16 v[6:9], v[146:149], v[186:189], v[6:9]
	v_mfma_f32_16x16x32_bf16 v[2:5], v[154:157], v[186:189], v[2:5]
	v_mfma_f32_16x16x32_bf16 v[54:57], v[150:153], v[166:169], v[54:57]
	v_mfma_f32_16x16x32_bf16 v[50:53], v[158:161], v[166:169], v[50:53]
	v_mfma_f32_16x16x32_bf16 v[38:41], v[150:153], v[174:177], v[38:41]
	v_mfma_f32_16x16x32_bf16 v[34:37], v[158:161], v[174:177], v[34:37]
	v_mfma_f32_16x16x32_bf16 v[22:25], v[150:153], v[182:185], v[22:25]
	v_mfma_f32_16x16x32_bf16 v[18:21], v[158:161], v[182:185], v[18:21]
	v_mfma_f32_16x16x32_bf16 v[6:9], v[150:153], v[190:193], v[6:9]
	v_mfma_f32_16x16x32_bf16 v[2:5], v[158:161], v[190:193], v[2:5]
	s_setprio 0
	s_barrier
	s_add_u32 s0, s0, 0x100
	s_addc_u32 s1, s1, 0
	s_add_u32 s6, s6, 0x100
	s_addc_u32 s7, s7, 0
	s_cmp_ge_i32 s36, s46
	s_mov_b32 s34, s36
	s_cbranch_scc0 .LBB0_298
	s_and_b64 vcc, exec, s[4:5]
	s_cbranch_vccnz .Lkl298_noa
	s_add_u32 s98, s28, 0x80
	s_addc_u32 s99, s29, 0
	v_lshl_add_u64 v[212:213], s[98:99], 0, v[210:211]
	s_add_i32 m0, s38, 0xc000
	s_nop 0
	global_load_lds_dwordx4 v[212:213], off
	v_lshl_add_u64 v[212:213], s[98:99], 0, v[208:209]
	s_add_i32 m0, s38, 0xe000
	s_nop 0
	global_load_lds_dwordx4 v[212:213], off

; #define PG8_STAGE(bufoff, gbase, voff) do { _Pragma("unroll") for (int _i = 0; _i < 2; ++_i) \
;         __builtin_amdgcn_global_load_lds((const unsigned*)((const char*)(gbase) + (voff)[_i]), (LAS unsigned*)(lds + (bufoff) + ldsw + _i * 8192), 16, 0, 0); } while (0)
; #define PG8_LDA(dst, b, h) do { _Pragma("unroll") for (int m = 0; m < 4; ++m) _Pragma("unroll") for (int k = 0; k < 2; ++k) dst[m][k] = *(const LAS bf16x8*)(lds + PG8_SA(b, h) + aoff + m * 2048 + k * 1024); } while (0)
; #define PG8_LDB(dst, b, h) do { _Pragma("unroll") for (int n = 0; n < 2; ++n) _Pragma("unroll") for (int k = 0; k < 2; ++k) dst[n][k] = *(const LAS bf16x8*)(lds + PG8_SB(b, h) + boff + n * 2048 + k * 1024); } while (0)
; #define PG8_MMA(ai, bj, At, Bt) do { __builtin_amdgcn_s_setprio(1); _Pragma("unroll") for (int m = 0; m < 4; ++m) _Pragma("unroll") for (int n = 0; n < 2; ++n) _Pragma("unroll") for (int k = 0; k < 2; ++k) \
;         acc[ai][bj][m][n] = __builtin_amdgcn_mfma_f32_16x16x32_bf16(Bt[n][k], At[m][k], acc[ai][bj][m][n], 0, 0, 0); __builtin_amdgcn_s_setprio(0); } while (0)
; #define PG8_WAIT_V(n) asm volatile("s_waitcnt vmcnt(" #n ")" ::: "memory")
; #define PG8_WAIT_L(n) asm volatile("s_waitcnt lgkmcnt(" #n ")" ::: "memory")
; #define PG8_BAR __builtin_amdgcn_s_barrier()
; #define PG8_SCHED __builtin_amdgcn_sched_barrier(0)
; template <class Epi>
; __device__ __forceinline__ void gemm_phase(LAS unsigned char* lds, const Gemm g, const StaticOrder& S, const Epi& E, const int tid) {
;     ...
;             PG8_LDB(B0, 1, 0); PG8_LDB(B1, 1, 1); PG8_SCHED; PG8_LDA(At, 1, 0); PG8_STAGE(PG8_SA(0, 1), a2 + hstepA, voffA);
;             PG8_WAIT_V(8); PG8_WAIT_L(0); PG8_BAR; PG8_MMA(0, 0, At, B0); PG8_MMA(0, 1, At, B1); PG8_BAR; PG8_SCHED;
.Lkl348_sp2:
	s_add_i32 s63, 0, 0x18000
	s_add_i32 s64, 0, 0x1c000
	v_add_u32_e32 v142, s63, v234
	v_add_u32_e32 v158, s64, v234
	ds_read_b128 v[130:133], v142
	ds_read_b128 v[134:137], v142 offset:1024
	ds_read_b128 v[138:141], v142 offset:2048
	ds_read_b128 v[142:145], v142 offset:3072
	ds_read_b128 v[146:149], v158
	ds_read_b128 v[150:153], v158 offset:1024
	ds_read_b128 v[154:157], v158 offset:2048
	ds_read_b128 v[158:161], v158 offset:3072
	s_add_u32 s38, s38, s12
	s_addc_u32 s39, s39, s13
	s_mov_b32 m0, s46
	v_lshl_add_u64 v[222:223], s[38:39], 0, v[202:203]
	ds_read_b128 v[162:165], v235 offset:32768
	ds_read_b128 v[166:169], v235 offset:33792
	ds_read_b128 v[170:173], v235 offset:34816
	ds_read_b128 v[174:177], v235 offset:35840
	ds_read_b128 v[178:181], v235 offset:36864
	ds_read_b128 v[182:185], v235 offset:37888
	ds_read_b128 v[186:189], v235 offset:38912
	ds_read_b128 v[190:193], v235 offset:39936
	global_load_lds_dwordx4 v[222:223], off
	v_lshl_add_u64 v[222:223], s[38:39], 0, v[204:205]
	s_mov_b32 m0, s47
	s_nop 0
	global_load_lds_dwordx4 v[222:223], off
	s_waitcnt vmcnt(8)
	s_waitcnt lgkmcnt(0)
	s_barrier
	s_setprio 1
	s_waitcnt lgkmcnt(0)
	v_mfma_f32_16x16x32_bf16 v[122:125], v[130:133], v[162:165], v[122:125]
	v_mfma_f32_16x16x32_bf16 v[126:129], v[138:141], v[162:165], v[126:129]
	v_mfma_f32_16x16x32_bf16 v[110:113], v[130:133], v[170:173], v[110:113]
	v_mfma_f32_16x16x32_bf16 v[106:109], v[138:141], v[170:173], v[106:109]
	v_mfma_f32_16x16x32_bf16 v[94:97], v[130:133], v[178:181], v[94:97]
	v_mfma_f32_16x16x32_bf16 v[90:93], v[138:141], v[178:181], v[90:93]
	v_mfma_f32_16x16x32_bf16 v[78:81], v[130:133], v[186:189], v[78:81]
	v_mfma_f32_16x16x32_bf16 v[74:77], v[138:141], v[186:189], v[74:77]
	v_mfma_f32_16x16x32_bf16 v[122:125], v[134:137], v[166:169], v[122:125]
	v_mfma_f32_16x16x32_bf16 v[126:129], v[142:145], v[166:169], v[126:129]
	v_mfma_f32_16x16x32_bf16 v[110:113], v[134:137], v[174:177], v[110:113]
	v_mfma_f32_16x16x32_bf16 v[106:109], v[142:145], v[174:177], v[106:109]
	v_mfma_f32_16x16x32_bf16 v[94:97], v[134:137], v[182:185], v[94:97]
	v_mfma_f32_16x16x32_bf16 v[90:93], v[142:145], v[182:185], v[90:93]
	v_mfma_f32_16x16x32_bf16 v[78:81], v[134:137], v[190:193], v[78:81]
	v_mfma_f32_16x16x32_bf16 v[74:77], v[142:145], v[190:193], v[74:77]
	s_setprio 0
	s_setprio 1
	v_mfma_f32_16x16x32_bf16 v[118:121], v[146:149], v[162:165], v[118:121]
	v_mfma_f32_16x16x32_bf16 v[114:117], v[154:157], v[162:165], v[114:117]
	v_mfma_f32_16x16x32_bf16 v[102:105], v[146:149], v[170:173], v[102:105]
	v_mfma_f32_16x16x32_bf16 v[98:101], v[154:157], v[170:173], v[98:101]
	v_mfma_f32_16x16x32_bf16 v[86:89], v[146:149], v[178:181], v[86:89]
	v_mfma_f32_16x16x32_bf16 v[82:85], v[154:157], v[178:181], v[82:85]
	v_mfma_f32_16x16x32_bf16 v[70:73], v[146:149], v[186:189], v[70:73]
	v_mfma_f32_16x16x32_bf16 v[66:69], v[154:157], v[186:189], v[66:69]
	v_mfma_f32_16x16x32_bf16 v[118:121], v[150:153], v[166:169], v[118:121]
	v_mfma_f32_16x16x32_bf16 v[114:117], v[158:161], v[166:169], v[114:117]
	v_mfma_f32_16x16x32_bf16 v[102:105], v[150:153], v[174:177], v[102:105]
	v_mfma_f32_16x16x32_bf16 v[98:101], v[158:161], v[174:177], v[98:101]
	v_mfma_f32_16x16x32_bf16 v[86:89], v[150:153], v[182:185], v[86:89]
	v_mfma_f32_16x16x32_bf16 v[82:85], v[158:161], v[182:185], v[82:85]
	v_mfma_f32_16x16x32_bf16 v[70:73], v[150:153], v[190:193], v[70:73]
	v_mfma_f32_16x16x32_bf16 v[66:69], v[158:161], v[190:193], v[66:69]
	s_setprio 0
	s_barrier
; #define PG8_STAGE(bufoff, gbase, voff) do { _Pragma("unroll") for (int _i = 0; _i < 2; ++_i) \
;         __builtin_amdgcn_global_load_lds((const unsigned*)((const char*)(gbase) + (voff)[_i]), (LAS unsigned*)(lds + (bufoff) + ldsw + _i * 8192), 16, 0, 0); } while (0)
; #define PG8_LDA(dst, b, h) do { _Pragma("unroll") for (int m = 0; m < 4; ++m) _Pragma("unroll") for (int k = 0; k < 2; ++k) dst[m][k] = *(const LAS bf16x8*)(lds + PG8_SA(b, h) + aoff + m * 2048 + k * 1024); } while (0)
; #define PG8_MMA(ai, bj, At, Bt) do { __builtin_amdgcn_s_setprio(1); _Pragma("unroll") for (int m = 0; m < 4; ++m) _Pragma("unroll") for (int n = 0; n < 2; ++n) _Pragma("unroll") for (int k = 0; k < 2; ++k) \
;         acc[ai][bj][m][n] = __builtin_amdgcn_mfma_f32_16x16x32_bf16(Bt[n][k], At[m][k], acc[ai][bj][m][n], 0, 0, 0); __builtin_amdgcn_s_setprio(0); } while (0)
; #define PG8_WAIT_V(n) asm volatile("s_waitcnt vmcnt(" #n ")" ::: "memory")
; #define PG8_WAIT_L(n) asm volatile("s_waitcnt lgkmcnt(" #n ")" ::: "memory")
; #define PG8_BAR __builtin_amdgcn_s_barrier()
; #define PG8_SCHED __builtin_amdgcn_sched_barrier(0)
; template <class Epi>
; __device__ __forceinline__ void gemm_phase(LAS unsigned char* lds, const Gemm g, const StaticOrder& S, const Epi& E, const int tid) {
;     ...
;             PG8_LDA(At, 1, 1); PG8_STAGE(PG8_SB(1, 0), b3, voffB); PG8_STAGE(PG8_SB(1, 1), b3 + hstepB, voffB); PG8_STAGE(PG8_SA(1, 0), a3, voffA);
;             PG8_WAIT_V(8); PG8_WAIT_L(0); PG8_BAR; PG8_MMA(1, 0, At, B0); PG8_MMA(1, 1, At, B1); PG8_BAR; PG8_SCHED;
	s_add_i32 s38, s63, s43
	v_lshl_add_u64 v[194:195], v[194:195], 0, s[80:81]
	s_mov_b32 m0, s38
	ds_read_b128 v[162:165], v235 offset:49152
	ds_read_b128 v[166:169], v235 offset:50176
	ds_read_b128 v[170:173], v235 offset:51200
	ds_read_b128 v[174:177], v235 offset:52224
	ds_read_b128 v[178:181], v235 offset:53248
	ds_read_b128 v[182:185], v235 offset:54272
	ds_read_b128 v[186:189], v235 offset:55296
	ds_read_b128 v[190:193], v235 offset:56320
	global_load_lds_dwordx4 v[194:195], off
	v_lshl_add_u64 v[194:195], v[212:213], 0, s[80:81]
	s_add_i32 m0, s38, 0x2000
	s_add_i32 s38, s64, s43
	global_load_lds_dwordx4 v[194:195], off
	v_lshl_add_u64 v[194:195], v[214:215], 0, s[80:81]
	s_mov_b32 m0, s38
	s_nop 0
	global_load_lds_dwordx4 v[194:195], off
	v_lshl_add_u64 v[194:195], v[216:217], 0, s[80:81]
	s_add_i32 m0, s38, 0x2000
	s_nop 0
	global_load_lds_dwordx4 v[194:195], off
	v_lshl_add_u64 v[194:195], v[218:219], 0, s[80:81]
	s_mov_b32 m0, s50
	s_nop 0
	global_load_lds_dwordx4 v[194:195], off
	v_lshl_add_u64 v[194:195], v[220:221], 0, s[80:81]
	s_mov_b32 m0, s51
	s_nop 0
	global_load_lds_dwordx4 v[194:195], off
	s_waitcnt vmcnt(8)
	s_waitcnt lgkmcnt(0)
	s_nop 0
	s_barrier
	s_setprio 1
	s_waitcnt lgkmcnt(0)
	v_mfma_f32_16x16x32_bf16 v[62:65], v[130:133], v[162:165], v[62:65]
	v_mfma_f32_16x16x32_bf16 v[58:61], v[138:141], v[162:165], v[58:61]
	v_mfma_f32_16x16x32_bf16 v[46:49], v[130:133], v[170:173], v[46:49]
	v_mfma_f32_16x16x32_bf16 v[42:45], v[138:141], v[170:173], v[42:45]
	v_mfma_f32_16x16x32_bf16 v[30:33], v[130:133], v[178:181], v[30:33]
	v_mfma_f32_16x16x32_bf16 v[26:29], v[138:141], v[178:181], v[26:29]
	v_mfma_f32_16x16x32_bf16 v[14:17], v[130:133], v[186:189], v[14:17]
	v_mfma_f32_16x16x32_bf16 v[10:13], v[138:141], v[186:189], v[10:13]
	v_mfma_f32_16x16x32_bf16 v[62:65], v[134:137], v[166:169], v[62:65]
	v_mfma_f32_16x16x32_bf16 v[58:61], v[142:145], v[166:169], v[58:61]
	v_mfma_f32_16x16x32_bf16 v[46:49], v[134:137], v[174:177], v[46:49]
	v_mfma_f32_16x16x32_bf16 v[42:45], v[142:145], v[174:177], v[42:45]
	v_mfma_f32_16x16x32_bf16 v[30:33], v[134:137], v[182:185], v[30:33]
	v_mfma_f32_16x16x32_bf16 v[26:29], v[142:145], v[182:185], v[26:29]
	v_mfma_f32_16x16x32_bf16 v[14:17], v[134:137], v[190:193], v[14:17]
	v_mfma_f32_16x16x32_bf16 v[10:13], v[142:145], v[190:193], v[10:13]
	s_setprio 0
	s_setprio 1
	v_mfma_f32_16x16x32_bf16 v[54:57], v[146:149], v[162:165], v[54:57]
	v_mfma_f32_16x16x32_bf16 v[50:53], v[154:157], v[162:165], v[50:53]
	v_mfma_f32_16x16x32_bf16 v[38:41], v[146:149], v[170:173], v[38:41]
	v_mfma_f32_16x16x32_bf16 v[34:37], v[154:157], v[170:173], v[34:37]
	v_mfma_f32_16x16x32_bf16 v[22:25], v[146:149], v[178:181], v[22:25]
	v_mfma_f32_16x16x32_bf16 v[18:21], v[154:157], v[178:181], v[18:21]
	v_mfma_f32_16x16x32_bf16 v[6:9], v[146:149], v[186:189], v[6:9]
	v_mfma_f32_16x16x32_bf16 v[2:5], v[154:157], v[186:189], v[2:5]
	v_mfma_f32_16x16x32_bf16 v[54:57], v[150:153], v[166:169], v[54:57]
	v_mfma_f32_16x16x32_bf16 v[50:53], v[158:161], v[166:169], v[50:53]
	v_mfma_f32_16x16x32_bf16 v[38:41], v[150:153], v[174:177], v[38:41]
	v_mfma_f32_16x16x32_bf16 v[34:37], v[158:161], v[174:177], v[34:37]
	v_mfma_f32_16x16x32_bf16 v[22:25], v[150:153], v[182:185], v[22:25]
	v_mfma_f32_16x16x32_bf16 v[18:21], v[158:161], v[182:185], v[18:21]
	v_mfma_f32_16x16x32_bf16 v[6:9], v[150:153], v[190:193], v[6:9]
	v_mfma_f32_16x16x32_bf16 v[2:5], v[158:161], v[190:193], v[2:5]
	s_setprio 0
	s_barrier
	s_add_u32 s0, s0, 0x100
	s_addc_u32 s1, s1, 0
	s_add_u32 s36, s36, 0x100
	s_addc_u32 s37, s37, 0
	s_cmp_ge_i32 s62, s53
	s_mov_b32 s38, s62
	s_cbranch_scc0 .LBB0_348

; #define PG8_STAGE(bufoff, gbase, voff) do { _Pragma("unroll") for (int _i = 0; _i < 2; ++_i) \
;         __builtin_amdgcn_global_load_lds((const unsigned*)((const char*)(gbase) + (voff)[_i]), (LAS unsigned*)(lds + (bufoff) + ldsw + _i * 8192), 16, 0, 0); } while (0)
; #define PG8_LDA(dst, b, h) do { _Pragma("unroll") for (int m = 0; m < 4; ++m) _Pragma("unroll") for (int k = 0; k < 2; ++k) dst[m][k] = *(const LAS bf16x8*)(lds + PG8_SA(b, h) + aoff + m * 2048 + k * 1024); } while (0)
; #define PG8_MMA(ai, bj, At, Bt) do { __builtin_amdgcn_s_setprio(1); _Pragma("unroll") for (int m = 0; m < 4; ++m) _Pragma("unroll") for (int n = 0; n < 2; ++n) _Pragma("unroll") for (int k = 0; k < 2; ++k) \
;         acc[ai][bj][m][n] = __builtin_amdgcn_mfma_f32_16x16x32_bf16(Bt[n][k], At[m][k], acc[ai][bj][m][n], 0, 0, 0); __builtin_amdgcn_s_setprio(0); } while (0)
; #define PG8_WAIT_V(n) asm volatile("s_waitcnt vmcnt(" #n ")" ::: "memory")
; #define PG8_WAIT_L(n) asm volatile("s_waitcnt lgkmcnt(" #n ")" ::: "memory")
; #define PG8_BAR __builtin_amdgcn_s_barrier()
; #define PG8_SCHED __builtin_amdgcn_sched_barrier(0)
; template <class Epi>
; __device__ __forceinline__ void gemm_phase(LAS unsigned char* lds, const Gemm g, const StaticOrder& S, const Epi& E, const int tid) {
;     ...
;             PG8_LDA(At, 1, 1); PG8_STAGE(PG8_SB(1, 0), b3, voffB); PG8_STAGE(PG8_SB(1, 1), b3 + hstepB, voffB); PG8_STAGE(PG8_SA(1, 0), a3, voffA);
;             PG8_WAIT_V(8); PG8_WAIT_L(0); PG8_BAR; PG8_MMA(1, 0, At, B0); PG8_MMA(1, 1, At, B1); PG8_BAR; PG8_SCHED;
.Lkl427_sp3:
	s_add_i32 s8, s11, s85
	v_lshl_add_u64 v[210:211], v[210:211], 0, s[80:81]
	s_mov_b32 m0, s8
	ds_read_b128 v[172:175], v223 offset:49152
	ds_read_b128 v[176:179], v223 offset:50176
	ds_read_b128 v[180:183], v223 offset:51200
	ds_read_b128 v[184:187], v223 offset:52224
	ds_read_b128 v[188:191], v223 offset:53248
	ds_read_b128 v[192:195], v223 offset:54272
	ds_read_b128 v[202:205], v223 offset:55296
	ds_read_b128 v[206:209], v223 offset:56320
	global_load_lds_dwordx4 v[210:211], off
	v_lshl_add_u64 v[210:211], v[212:213], 0, s[80:81]
	s_add_i32 m0, s8, 0x2000
	s_add_i32 s8, s12, s85
	global_load_lds_dwordx4 v[210:211], off
	v_lshl_add_u64 v[210:211], v[214:215], 0, s[80:81]
	s_mov_b32 m0, s8
	s_nop 0
	global_load_lds_dwordx4 v[210:211], off
	v_lshl_add_u64 v[210:211], v[216:217], 0, s[80:81]
	s_add_i32 m0, s8, 0x2000
	s_nop 0
	global_load_lds_dwordx4 v[210:211], off
	v_lshl_add_u64 v[210:211], v[218:219], 0, s[80:81]
	s_mov_b32 m0, s36
	s_nop 0
	global_load_lds_dwordx4 v[210:211], off
	v_lshl_add_u64 v[210:211], v[220:221], 0, s[80:81]
	s_mov_b32 m0, s37
	s_nop 0
	global_load_lds_dwordx4 v[210:211], off
	s_waitcnt vmcnt(8)
	s_waitcnt lgkmcnt(0)
	s_nop 0
	s_barrier
	s_setprio 1
	s_waitcnt lgkmcnt(0)
	v_mfma_f32_16x16x32_bf16 v[62:65], v[66:69], v[172:175], v[62:65]
	v_mfma_f32_16x16x32_bf16 v[58:61], v[74:77], v[172:175], v[58:61]
	v_mfma_f32_16x16x32_bf16 v[46:49], v[66:69], v[180:183], v[46:49]
	v_mfma_f32_16x16x32_bf16 v[42:45], v[74:77], v[180:183], v[42:45]
	v_mfma_f32_16x16x32_bf16 v[30:33], v[66:69], v[188:191], v[30:33]
	v_mfma_f32_16x16x32_bf16 v[26:29], v[74:77], v[188:191], v[26:29]
	v_mfma_f32_16x16x32_bf16 v[14:17], v[66:69], v[202:205], v[14:17]
	v_mfma_f32_16x16x32_bf16 v[10:13], v[74:77], v[202:205], v[10:13]
	v_mfma_f32_16x16x32_bf16 v[62:65], v[70:73], v[176:179], v[62:65]
	v_mfma_f32_16x16x32_bf16 v[58:61], v[78:81], v[176:179], v[58:61]
	v_mfma_f32_16x16x32_bf16 v[46:49], v[70:73], v[184:187], v[46:49]
	v_mfma_f32_16x16x32_bf16 v[42:45], v[78:81], v[184:187], v[42:45]
	v_mfma_f32_16x16x32_bf16 v[30:33], v[70:73], v[192:195], v[30:33]
	v_mfma_f32_16x16x32_bf16 v[26:29], v[78:81], v[192:195], v[26:29]
	v_mfma_f32_16x16x32_bf16 v[14:17], v[70:73], v[206:209], v[14:17]
	v_mfma_f32_16x16x32_bf16 v[10:13], v[78:81], v[206:209], v[10:13]
	s_setprio 0
	s_setprio 1
	v_mfma_f32_16x16x32_bf16 v[54:57], v[156:159], v[172:175], v[54:57]
	v_mfma_f32_16x16x32_bf16 v[50:53], v[164:167], v[172:175], v[50:53]
	v_mfma_f32_16x16x32_bf16 v[38:41], v[156:159], v[180:183], v[38:41]
	v_mfma_f32_16x16x32_bf16 v[34:37], v[164:167], v[180:183], v[34:37]
	v_mfma_f32_16x16x32_bf16 v[22:25], v[156:159], v[188:191], v[22:25]
	v_mfma_f32_16x16x32_bf16 v[18:21], v[164:167], v[188:191], v[18:21]
	v_mfma_f32_16x16x32_bf16 v[6:9], v[156:159], v[202:205], v[6:9]
	v_mfma_f32_16x16x32_bf16 v[2:5], v[164:167], v[202:205], v[2:5]
	v_mfma_f32_16x16x32_bf16 v[54:57], v[160:163], v[176:179], v[54:57]
	v_mfma_f32_16x16x32_bf16 v[50:53], v[168:171], v[176:179], v[50:53]
	v_mfma_f32_16x16x32_bf16 v[38:41], v[160:163], v[184:187], v[38:41]
	v_mfma_f32_16x16x32_bf16 v[34:37], v[168:171], v[184:187], v[34:37]
	v_mfma_f32_16x16x32_bf16 v[22:25], v[160:163], v[192:195], v[22:25]
	v_mfma_f32_16x16x32_bf16 v[18:21], v[168:171], v[192:195], v[18:21]
	v_mfma_f32_16x16x32_bf16 v[6:9], v[160:163], v[206:209], v[6:9]
	v_mfma_f32_16x16x32_bf16 v[2:5], v[168:171], v[206:209], v[2:5]
	s_setprio 0
	s_barrier
	s_add_u32 s0, s0, 0x100
	s_addc_u32 s1, s1, 0
	s_add_u32 s6, s6, 0x100
	s_addc_u32 s7, s7, 0
	s_cmp_ge_i32 s10, s35
	s_mov_b32 s8, s10
	s_cbranch_scc0 .LBB0_427
	s_and_b64 vcc, exec, s[4:5]
	s_cbranch_vccnz .Lkl427_noa
	s_add_u32 s98, s62, 0x80
	s_addc_u32 s99, s63, 0
	v_lshl_add_u64 v[210:211], s[98:99], 0, v[154:155]
	s_add_i32 m0, s44, 0xc000
	s_nop 0
	global_load_lds_dwordx4 v[210:211], off
	v_lshl_add_u64 v[210:211], s[98:99], 0, v[152:153]
	s_add_i32 m0, s44, 0xe000
	s_nop 0
	global_load_lds_dwordx4 v[210:211], off

; #define PG8_STAGE(bufoff, gbase, voff) do { _Pragma("unroll") for (int _i = 0; _i < 2; ++_i) \
;         __builtin_amdgcn_global_load_lds((const unsigned*)((const char*)(gbase) + (voff)[_i]), (LAS unsigned*)(lds + (bufoff) + ldsw + _i * 8192), 16, 0, 0); } while (0)
; #define PG8_LDA(dst, b, h) do { _Pragma("unroll") for (int m = 0; m < 4; ++m) _Pragma("unroll") for (int k = 0; k < 2; ++k) dst[m][k] = *(const LAS bf16x8*)(lds + PG8_SA(b, h) + aoff + m * 2048 + k * 1024); } while (0)
; #define PG8_MMA(ai, bj, At, Bt) do { __builtin_amdgcn_s_setprio(1); _Pragma("unroll") for (int m = 0; m < 4; ++m) _Pragma("unroll") for (int n = 0; n < 2; ++n) _Pragma("unroll") for (int k = 0; k < 2; ++k) \
;         acc[ai][bj][m][n] = __builtin_amdgcn_mfma_f32_16x16x32_bf16(Bt[n][k], At[m][k], acc[ai][bj][m][n], 0, 0, 0); __builtin_amdgcn_s_setprio(0); } while (0)
; #define PG8_WAIT_V(n) asm volatile("s_waitcnt vmcnt(" #n ")" ::: "memory")
; #define PG8_WAIT_L(n) asm volatile("s_waitcnt lgkmcnt(" #n ")" ::: "memory")
; #define PG8_BAR __builtin_amdgcn_s_barrier()
; #define PG8_SCHED __builtin_amdgcn_sched_barrier(0)
; template <class Epi>
; __device__ __forceinline__ void gemm_phase(LAS unsigned char* lds, const Gemm g, const StaticOrder& S, const Epi& E, const int tid) {
;     ...
;             PG8_LDA(At, 1, 1); PG8_STAGE(PG8_SB(1, 0), b3, voffB); PG8_STAGE(PG8_SB(1, 1), b3 + hstepB, voffB); PG8_STAGE(PG8_SA(1, 0), a3, voffA);
;             PG8_WAIT_V(8); PG8_WAIT_L(0); PG8_BAR; PG8_MMA(1, 0, At, B0); PG8_MMA(1, 1, At, B1); PG8_BAR; PG8_SCHED;
.Lkl652_sp3:
	s_add_i32 s8, s11, s53
	v_lshl_add_u64 v[178:179], v[178:179], 0, s[80:81]
	s_mov_b32 m0, s8
	ds_read_b128 v[162:165], v205 offset:49152
	ds_read_b128 v[166:169], v205 offset:50176
	ds_read_b128 v[170:173], v205 offset:51200
	ds_read_b128 v[174:177], v205 offset:52224
	ds_read_b128 v[192:195], v205 offset:53248
	ds_read_b128 v[206:209], v205 offset:54272
	ds_read_b128 v[210:213], v205 offset:55296
	ds_read_b128 v[214:217], v205 offset:56320
	global_load_lds_dwordx4 v[178:179], off
	v_lshl_add_u64 v[178:179], v[202:203], 0, s[80:81]
	s_add_i32 m0, s8, 0x2000
	s_add_i32 s8, s43, s53
	global_load_lds_dwordx4 v[178:179], off
	v_lshl_add_u64 v[178:179], v[218:219], 0, s[80:81]
	s_mov_b32 m0, s8
	s_nop 0
	global_load_lds_dwordx4 v[178:179], off
	v_lshl_add_u64 v[178:179], v[220:221], 0, s[80:81]
	s_add_i32 m0, s8, 0x2000
	s_nop 0
	global_load_lds_dwordx4 v[178:179], off
	v_lshl_add_u64 v[178:179], v[222:223], 0, s[80:81]
	s_mov_b32 m0, s62
	s_nop 0
	global_load_lds_dwordx4 v[178:179], off
	v_lshl_add_u64 v[178:179], v[224:225], 0, s[80:81]
	s_mov_b32 m0, s63
	s_nop 0
	global_load_lds_dwordx4 v[178:179], off
	s_waitcnt vmcnt(8)
	s_waitcnt lgkmcnt(0)
	s_nop 0
	s_barrier
	s_setprio 1
	s_waitcnt lgkmcnt(0)
	v_mfma_f32_16x16x32_bf16 v[46:49], v[130:133], v[162:165], v[46:49]
	v_mfma_f32_16x16x32_bf16 v[30:33], v[138:141], v[162:165], v[30:33]
	v_mfma_f32_16x16x32_bf16 v[38:41], v[130:133], v[170:173], v[38:41]
	v_mfma_f32_16x16x32_bf16 v[18:21], v[138:141], v[170:173], v[18:21]
	v_mfma_f32_16x16x32_bf16 v[50:53], v[130:133], v[192:195], v[50:53]
	v_mfma_f32_16x16x32_bf16 v[2:5], v[138:141], v[192:195], v[2:5]
	v_mfma_f32_16x16x32_bf16 v[74:77], v[130:133], v[210:213], v[74:77]
	v_mfma_f32_16x16x32_bf16 v[10:13], v[138:141], v[210:213], v[10:13]
	v_mfma_f32_16x16x32_bf16 v[46:49], v[134:137], v[166:169], v[46:49]
	v_mfma_f32_16x16x32_bf16 v[30:33], v[142:145], v[166:169], v[30:33]
	v_mfma_f32_16x16x32_bf16 v[38:41], v[134:137], v[174:177], v[38:41]
	v_mfma_f32_16x16x32_bf16 v[18:21], v[142:145], v[174:177], v[18:21]
	v_mfma_f32_16x16x32_bf16 v[50:53], v[134:137], v[206:209], v[50:53]
	v_mfma_f32_16x16x32_bf16 v[2:5], v[142:145], v[206:209], v[2:5]
	v_mfma_f32_16x16x32_bf16 v[74:77], v[134:137], v[214:217], v[74:77]
	v_mfma_f32_16x16x32_bf16 v[10:13], v[142:145], v[214:217], v[10:13]
	s_setprio 0
	s_setprio 1
	v_mfma_f32_16x16x32_bf16 v[42:45], v[146:149], v[162:165], v[42:45]
	v_mfma_f32_16x16x32_bf16 v[34:37], v[154:157], v[162:165], v[34:37]
	v_mfma_f32_16x16x32_bf16 v[26:29], v[146:149], v[170:173], v[26:29]
	v_mfma_f32_16x16x32_bf16 v[22:25], v[154:157], v[170:173], v[22:25]
	v_mfma_f32_16x16x32_bf16 v[54:57], v[146:149], v[192:195], v[54:57]
	v_mfma_f32_16x16x32_bf16 v[6:9], v[154:157], v[192:195], v[6:9]
	v_mfma_f32_16x16x32_bf16 v[78:81], v[146:149], v[210:213], v[78:81]
	v_mfma_f32_16x16x32_bf16 v[14:17], v[154:157], v[210:213], v[14:17]
	v_mfma_f32_16x16x32_bf16 v[42:45], v[150:153], v[166:169], v[42:45]
	v_mfma_f32_16x16x32_bf16 v[34:37], v[158:161], v[166:169], v[34:37]
	v_mfma_f32_16x16x32_bf16 v[26:29], v[150:153], v[174:177], v[26:29]
	v_mfma_f32_16x16x32_bf16 v[22:25], v[158:161], v[174:177], v[22:25]
	v_mfma_f32_16x16x32_bf16 v[54:57], v[150:153], v[206:209], v[54:57]
	v_mfma_f32_16x16x32_bf16 v[6:9], v[158:161], v[206:209], v[6:9]
	v_mfma_f32_16x16x32_bf16 v[78:81], v[150:153], v[214:217], v[78:81]
	v_mfma_f32_16x16x32_bf16 v[14:17], v[158:161], v[214:217], v[14:17]
	s_setprio 0
	s_barrier
	s_add_u32 s21, s21, 0x100
	s_addc_u32 s42, s42, 0
	s_add_u32 s6, s6, 0x100
	s_addc_u32 s7, s7, 0
	s_cmp_ge_i32 s10, s64
	s_mov_b32 s8, s10
	s_cbranch_scc0 .LBB0_652
	s_and_b64 vcc, exec, s[4:5]
	s_cbranch_vccnz .Lkl652_noa
	s_add_u32 s98, s38, 0x80
	s_addc_u32 s99, s39, 0
	v_lshl_add_u64 v[178:179], s[98:99], 0, v[190:191]
	s_add_i32 m0, s54, 0xc000
	s_nop 0
	global_load_lds_dwordx4 v[178:179], off
	v_lshl_add_u64 v[178:179], s[98:99], 0, v[188:189]
	s_add_i32 m0, s54, 0xe000
	s_nop 0
	global_load_lds_dwordx4 v[178:179], off
